# w24 + dropped the conservative vmcnt(0) in the P6 tile header (prologue DMA stays in flight into the first K iteration)
# baseline (speedup 1.0000x reference)
; template <class Epi, class Sched, bool ALIGN_EPI = false, bool SP2 = false>
; __device__ __forceinline__ void gemm_phase(PG8_LAS unsigned char* lds, const Gemm g, const Sched& S, const Epi& E) {
;     ...
;         const bool has_next = S.next(ui + 1, nxt);
;         const char* nA = has_next ? (const char*)g.A + (size_t)nxt.pm * tstep : cA; const char* nB = has_next ? (const char*)g.Bt + (size_t)nxt.pn * tstep : cB;
;     ...
; #pragma unroll
;         for (int a = 0; a < 2; ++a)
; #pragma unroll
;             for (int b = 0; b < 2; ++b)
; #pragma unroll
;                 for (int m = 0; m < 4; ++m)
; #pragma unroll
;                     for (int n = 0; n < 2; ++n) acc[a][b][m][n] = (f32x4){0.f, 0.f, 0.f, 0.f};
;         cur = nxt; cA = nA; cB = nB; ++ui;
.LBB0_541:
	s_ashr_i32 s51, s50, 31
	s_lshl_b64 s[14:15], s[50:51], 19
	s_add_u32 s52, s2, s14
	s_addc_u32 s53, s3, s15
	s_and_b64 s[14:15], s[38:39], exec
	s_cselect_b32 s51, s53, s67
	s_cselect_b32 s89, s52, s66
	s_ashr_i32 s49, s48, 31
	s_lshl_b64 s[14:15], s[48:49], 19
	s_add_u32 s54, s74, s14
	s_addc_u32 s55, s75, s15
	s_and_b64 s[14:15], s[38:39], exec
	s_cselect_b32 s49, s55, s77
	s_cselect_b32 s90, s54, s76
	s_add_u32 s66, s66, 0x40080
	s_addc_u32 s67, s67, 0
	s_add_u32 s76, s76, 0x100
	v_mov_b32_e32 v0, 0
	s_addc_u32 s33, s77, 0
	s_mov_b32 s16, -2
	s_waitcnt lgkmcnt(0)
	v_mov_b32_e32 v1, v0
	v_mov_b64_e32 v[2:3], 0
	v_mov_b64_e32 v[4:5], 0
	v_mov_b64_e32 v[6:7], 0
	v_mov_b64_e32 v[16:17], 0
	v_mov_b64_e32 v[18:19], 0
	v_mov_b64_e32 v[20:21], 0
	v_mov_b64_e32 v[22:23], 0
	v_mov_b64_e32 v[32:33], 0
	v_mov_b64_e32 v[34:35], 0
	v_mov_b64_e32 v[36:37], 0
	v_mov_b64_e32 v[38:39], 0
	v_mov_b64_e32 v[48:49], 0
	v_mov_b64_e32 v[50:51], 0
	v_mov_b64_e32 v[52:53], 0
	v_mov_b64_e32 v[54:55], 0
	v_mov_b64_e32 v[8:9], 0
	v_mov_b64_e32 v[10:11], 0
	v_mov_b64_e32 v[12:13], 0
	v_mov_b64_e32 v[14:15], 0
	v_mov_b64_e32 v[24:25], 0
	v_mov_b64_e32 v[26:27], 0
	v_mov_b64_e32 v[28:29], 0
	v_mov_b64_e32 v[30:31], 0
	v_mov_b64_e32 v[40:41], 0
	v_mov_b64_e32 v[42:43], 0
	v_mov_b64_e32 v[44:45], 0
	v_mov_b64_e32 v[46:47], 0
	v_mov_b64_e32 v[56:57], 0
	v_mov_b64_e32 v[58:59], 0
	v_mov_b64_e32 v[60:61], 0
	v_mov_b64_e32 v[62:63], 0
	v_mov_b64_e32 v[64:65], 0
	v_mov_b64_e32 v[66:67], 0
	v_mov_b64_e32 v[68:69], 0
	v_mov_b64_e32 v[70:71], 0
	v_mov_b64_e32 v[96:97], 0
	v_mov_b64_e32 v[98:99], 0
	v_mov_b64_e32 v[100:101], 0
	v_mov_b64_e32 v[102:103], 0
	v_mov_b64_e32 v[112:113], 0
	v_mov_b64_e32 v[114:115], 0
	v_mov_b64_e32 v[116:117], 0
	v_mov_b64_e32 v[118:119], 0
	v_mov_b64_e32 v[128:129], 0
	v_mov_b64_e32 v[130:131], 0
	v_mov_b64_e32 v[132:133], 0
	v_mov_b64_e32 v[134:135], 0
	v_mov_b64_e32 v[80:81], 0
	v_mov_b64_e32 v[82:83], 0
	v_mov_b64_e32 v[84:85], 0
	v_mov_b64_e32 v[86:87], 0
	v_mov_b64_e32 v[104:105], 0
	v_mov_b64_e32 v[106:107], 0
	v_mov_b64_e32 v[108:109], 0
	v_mov_b64_e32 v[110:111], 0
	v_mov_b64_e32 v[120:121], 0
	v_mov_b64_e32 v[122:123], 0
	v_mov_b64_e32 v[124:125], 0
	v_mov_b64_e32 v[126:127], 0
	v_mov_b64_e32 v[136:137], 0
	v_mov_b64_e32 v[138:139], 0
	v_mov_b64_e32 v[140:141], 0
	v_mov_b64_e32 v[142:143], 0
